# phase-14 epilogue: row-scale loads hoisted (8 loads, one wait) on top of dwordx4 stores
# speedup vs baseline: 1.0154x; 1.0066x over previous
.LBB0_2705:
	v_lshl_add_u32 v144, s26, 8, v1
	v_ashrrev_i32_e32 v145, 31, v144
	s_nop 15
	s_nop 15
	v_bfe_u32 v234, v206, 4, 1
	v_mul_u32_u24_e32 v234, 24, v234
	v_mov_b32_e32 v235, 0
	v_lshl_add_u64 v[152:153], v[144:145], 2, s[12:13]
	global_load_dword v154, v[152:153], off
	global_load_dword v236, v[152:153], off
	global_load_dword v237, v[152:153], off offset:64
	global_load_dword v238, v[152:153], off offset:128
	global_load_dword v239, v[152:153], off offset:192
	global_load_dword v240, v[152:153], off offset:512
	global_load_dword v241, v[152:153], off offset:576
	global_load_dword v242, v[152:153], off offset:640
	global_load_dword v243, v[152:153], off offset:704
	s_lshl_b32 s0, s27, 8
	v_mov_b64_e32 v[146:147], s[10:11]
	s_ashr_i32 s1, s0, 31
	v_mad_i64_i32 v[156:157], s[26:27], v144, s52, v[146:147]
	s_lshl_b64 s[26:27], s[0:1], 1
	s_nop 0
	v_lshl_add_u64 v[156:157], v[156:157], 0, s[26:27]
	v_lshl_add_u64 v[156:157], v[156:157], 0, v[134:135]
	s_andn2_b64 vcc, exec, s[4:5]
	s_mov_b64 s[4:5], -1
	s_waitcnt vmcnt(0)
	v_pk_mul_f32 v[126:127], v[126:127], v[154:155] op_sel_hi:[1,0]
	v_pk_mul_f32 v[128:129], v[128:129], v[154:155] op_sel_hi:[1,0]
	v_cvt_pk_bf16_f32 v224, v126, v127
	s_nop 0
	v_cvt_pk_bf16_f32 v225, v128, v129
	s_nop 0
	v_mov_b32_e32 v126, v236
	s_nop 0
	v_pk_mul_f32 v[122:123], v[122:123], v[126:127] op_sel_hi:[1,0]
	v_pk_mul_f32 v[124:125], v[124:125], v[126:127] op_sel_hi:[1,0]
	v_cvt_pk_bf16_f32 v226, v122, v123
	s_nop 0
	v_cvt_pk_bf16_f32 v227, v124, v125
	s_nop 1
	v_permlane16_swap_b32_e32 v224, v226
	v_permlane16_swap_b32_e32 v225, v227
	v_lshl_add_u64 v[232:233], v[156:157], 0, v[234:235]
	global_store_dwordx4 v[232:233], v[224:227], off
	v_mov_b32_e32 v122, v236
	s_nop 0
	v_pk_mul_f32 v[118:119], v[118:119], v[122:123] op_sel_hi:[1,0]
	v_pk_mul_f32 v[120:121], v[120:121], v[122:123] op_sel_hi:[1,0]
	v_cvt_pk_bf16_f32 v228, v118, v119
	s_nop 0
	v_cvt_pk_bf16_f32 v229, v120, v121
	s_nop 0
	v_mov_b32_e32 v118, v236
	v_or_b32_e32 v120, 16, v144
	v_ashrrev_i32_e32 v121, 31, v120
	v_lshl_add_u64 v[122:123], v[120:121], 2, s[12:13]
	s_nop 0
	v_pk_mul_f32 v[110:111], v[110:111], v[118:119] op_sel_hi:[1,0]
	v_pk_mul_f32 v[112:113], v[112:113], v[118:119] op_sel_hi:[1,0]
	v_cvt_pk_bf16_f32 v230, v110, v111
	s_nop 0
	v_cvt_pk_bf16_f32 v231, v112, v113
	s_nop 1
	v_permlane16_swap_b32_e32 v228, v230
	v_permlane16_swap_b32_e32 v229, v231
	v_lshl_add_u64 v[232:233], v[156:157], 0, v[234:235]
	global_store_dwordx4 v[232:233], v[228:231], off offset:256
	v_mov_b32_e32 v110, v237
	v_mad_i64_i32 v[112:113], s[0:1], v120, s52, v[146:147]
	v_lshl_add_u64 v[112:113], v[112:113], 0, s[26:27]
	v_lshl_add_u64 v[112:113], v[112:113], 0, v[134:135]
	s_nop 0
	v_pk_mul_f32 v[116:117], v[116:117], v[110:111] op_sel_hi:[1,0]
	v_pk_mul_f32 v[110:111], v[114:115], v[110:111] op_sel_hi:[1,0]
	s_nop 0
	v_cvt_pk_bf16_f32 v224, v110, v111
	v_cvt_pk_bf16_f32 v225, v116, v117
	s_nop 0
	v_mov_b32_e32 v110, v237
	s_nop 0
	v_pk_mul_f32 v[106:107], v[106:107], v[110:111] op_sel_hi:[1,0]
	v_pk_mul_f32 v[108:109], v[108:109], v[110:111] op_sel_hi:[1,0]
	v_cvt_pk_bf16_f32 v226, v106, v107
	s_nop 0
	v_cvt_pk_bf16_f32 v227, v108, v109
	s_nop 1
	v_permlane16_swap_b32_e32 v224, v226
	v_permlane16_swap_b32_e32 v225, v227
	v_lshl_add_u64 v[232:233], v[112:113], 0, v[234:235]
	global_store_dwordx4 v[232:233], v[224:227], off
	v_mov_b32_e32 v106, v237
	s_nop 0
	v_pk_mul_f32 v[102:103], v[102:103], v[106:107] op_sel_hi:[1,0]
	v_pk_mul_f32 v[104:105], v[104:105], v[106:107] op_sel_hi:[1,0]
	v_cvt_pk_bf16_f32 v228, v102, v103
	s_nop 0
	v_cvt_pk_bf16_f32 v229, v104, v105
	s_nop 0
	v_mov_b32_e32 v102, v237
	v_or_b32_e32 v104, 32, v144
	v_ashrrev_i32_e32 v105, 31, v104
	v_lshl_add_u64 v[106:107], v[104:105], 2, s[12:13]
	s_nop 0
	v_pk_mul_f32 v[94:95], v[94:95], v[102:103] op_sel_hi:[1,0]
	v_pk_mul_f32 v[96:97], v[96:97], v[102:103] op_sel_hi:[1,0]
	v_cvt_pk_bf16_f32 v230, v94, v95
	s_nop 0
	v_cvt_pk_bf16_f32 v231, v96, v97
	s_nop 1
	v_permlane16_swap_b32_e32 v228, v230
	v_permlane16_swap_b32_e32 v229, v231
	v_lshl_add_u64 v[232:233], v[112:113], 0, v[234:235]
	global_store_dwordx4 v[232:233], v[228:231], off offset:256
	v_mov_b32_e32 v94, v238
	v_mad_i64_i32 v[96:97], s[0:1], v104, s52, v[146:147]
	v_lshl_add_u64 v[96:97], v[96:97], 0, s[26:27]
	v_lshl_add_u64 v[96:97], v[96:97], 0, v[134:135]
	s_nop 0
	v_pk_mul_f32 v[100:101], v[100:101], v[94:95] op_sel_hi:[1,0]
	v_pk_mul_f32 v[94:95], v[98:99], v[94:95] op_sel_hi:[1,0]
	s_nop 0
	v_cvt_pk_bf16_f32 v224, v94, v95
	v_cvt_pk_bf16_f32 v225, v100, v101
	s_nop 0
	v_mov_b32_e32 v94, v238
	s_nop 0
	v_pk_mul_f32 v[90:91], v[90:91], v[94:95] op_sel_hi:[1,0]
	v_pk_mul_f32 v[92:93], v[92:93], v[94:95] op_sel_hi:[1,0]
	v_cvt_pk_bf16_f32 v226, v90, v91
	s_nop 0
	v_cvt_pk_bf16_f32 v227, v92, v93
	s_nop 1
	v_permlane16_swap_b32_e32 v224, v226
	v_permlane16_swap_b32_e32 v225, v227
	v_lshl_add_u64 v[232:233], v[96:97], 0, v[234:235]
	global_store_dwordx4 v[232:233], v[224:227], off
	v_mov_b32_e32 v90, v238
	s_nop 0
	v_pk_mul_f32 v[86:87], v[86:87], v[90:91] op_sel_hi:[1,0]
	v_pk_mul_f32 v[88:89], v[88:89], v[90:91] op_sel_hi:[1,0]
	v_cvt_pk_bf16_f32 v228, v86, v87
	s_nop 0
	v_cvt_pk_bf16_f32 v229, v88, v89
	s_nop 0
	v_mov_b32_e32 v86, v238
	v_or_b32_e32 v88, 48, v144
	v_ashrrev_i32_e32 v89, 31, v88
	v_lshl_add_u64 v[90:91], v[88:89], 2, s[12:13]
	s_nop 0
	v_pk_mul_f32 v[78:79], v[78:79], v[86:87] op_sel_hi:[1,0]
	v_pk_mul_f32 v[80:81], v[80:81], v[86:87] op_sel_hi:[1,0]
	v_cvt_pk_bf16_f32 v230, v78, v79
	s_nop 0
	v_cvt_pk_bf16_f32 v231, v80, v81
	s_nop 1
	v_permlane16_swap_b32_e32 v228, v230
	v_permlane16_swap_b32_e32 v229, v231
	v_lshl_add_u64 v[232:233], v[96:97], 0, v[234:235]
	global_store_dwordx4 v[232:233], v[228:231], off offset:256
	v_mov_b32_e32 v78, v239
	v_mad_i64_i32 v[80:81], s[0:1], v88, s52, v[146:147]
	v_lshl_add_u64 v[80:81], v[80:81], 0, s[26:27]
	v_lshl_add_u64 v[80:81], v[80:81], 0, v[134:135]
	s_nop 0
	v_pk_mul_f32 v[84:85], v[84:85], v[78:79] op_sel_hi:[1,0]
	v_pk_mul_f32 v[78:79], v[82:83], v[78:79] op_sel_hi:[1,0]
	s_nop 0
	v_cvt_pk_bf16_f32 v224, v78, v79
	v_cvt_pk_bf16_f32 v225, v84, v85
	s_nop 0
	v_mov_b32_e32 v78, v239
	s_nop 0
	v_pk_mul_f32 v[74:75], v[74:75], v[78:79] op_sel_hi:[1,0]
	v_pk_mul_f32 v[76:77], v[76:77], v[78:79] op_sel_hi:[1,0]
	v_cvt_pk_bf16_f32 v226, v74, v75
	s_nop 0
	v_cvt_pk_bf16_f32 v227, v76, v77
	s_nop 1
	v_permlane16_swap_b32_e32 v224, v226
	v_permlane16_swap_b32_e32 v225, v227
	v_lshl_add_u64 v[232:233], v[80:81], 0, v[234:235]
	global_store_dwordx4 v[232:233], v[224:227], off
	v_mov_b32_e32 v74, v239
	s_nop 0
	v_pk_mul_f32 v[70:71], v[70:71], v[74:75] op_sel_hi:[1,0]
	v_pk_mul_f32 v[72:73], v[72:73], v[74:75] op_sel_hi:[1,0]
	v_cvt_pk_bf16_f32 v228, v70, v71
	s_nop 0
	v_cvt_pk_bf16_f32 v229, v72, v73
	s_nop 0
	v_mov_b32_e32 v70, v239
	v_add_u32_e32 v72, 0x80, v144
	v_ashrrev_i32_e32 v73, 31, v72
	v_lshl_add_u64 v[74:75], v[72:73], 2, s[12:13]
	s_nop 0
	v_pk_mul_f32 v[66:67], v[66:67], v[70:71] op_sel_hi:[1,0]
	v_pk_mul_f32 v[68:69], v[68:69], v[70:71] op_sel_hi:[1,0]
	v_cvt_pk_bf16_f32 v230, v66, v67
	s_nop 0
	v_cvt_pk_bf16_f32 v231, v68, v69
	s_nop 1
	v_permlane16_swap_b32_e32 v228, v230
	v_permlane16_swap_b32_e32 v229, v231
	v_lshl_add_u64 v[232:233], v[80:81], 0, v[234:235]
	global_store_dwordx4 v[232:233], v[228:231], off offset:256
	v_mov_b32_e32 v66, v240
	v_mad_i64_i32 v[68:69], s[0:1], v72, s52, v[146:147]
	v_lshl_add_u64 v[68:69], v[68:69], 0, s[26:27]
	v_lshl_add_u64 v[68:69], v[68:69], 0, v[134:135]
	s_nop 0
	v_pk_mul_f32 v[62:63], v[62:63], v[66:67] op_sel_hi:[1,0]
	v_pk_mul_f32 v[64:65], v[64:65], v[66:67] op_sel_hi:[1,0]
	v_cvt_pk_bf16_f32 v224, v62, v63
	s_nop 0
	v_cvt_pk_bf16_f32 v225, v64, v65
	s_nop 0
	v_mov_b32_e32 v62, v240
	s_nop 0
	v_pk_mul_f32 v[58:59], v[58:59], v[62:63] op_sel_hi:[1,0]
	v_pk_mul_f32 v[60:61], v[60:61], v[62:63] op_sel_hi:[1,0]
	v_cvt_pk_bf16_f32 v226, v58, v59
	s_nop 0
	v_cvt_pk_bf16_f32 v227, v60, v61
	s_nop 1
	v_permlane16_swap_b32_e32 v224, v226
	v_permlane16_swap_b32_e32 v225, v227
	v_lshl_add_u64 v[232:233], v[68:69], 0, v[234:235]
	global_store_dwordx4 v[232:233], v[224:227], off
	v_mov_b32_e32 v58, v240
	s_nop 0
	v_pk_mul_f32 v[54:55], v[54:55], v[58:59] op_sel_hi:[1,0]
	v_pk_mul_f32 v[56:57], v[56:57], v[58:59] op_sel_hi:[1,0]
	v_cvt_pk_bf16_f32 v228, v54, v55
	s_nop 0
	v_cvt_pk_bf16_f32 v229, v56, v57
	s_nop 0
	v_mov_b32_e32 v54, v240
	v_add_u32_e32 v56, 0x90, v144
	v_ashrrev_i32_e32 v57, 31, v56
	v_lshl_add_u64 v[58:59], v[56:57], 2, s[12:13]
	s_nop 0
	v_pk_mul_f32 v[46:47], v[46:47], v[54:55] op_sel_hi:[1,0]
	v_pk_mul_f32 v[48:49], v[48:49], v[54:55] op_sel_hi:[1,0]
	v_cvt_pk_bf16_f32 v230, v46, v47
	s_nop 0
	v_cvt_pk_bf16_f32 v231, v48, v49
	s_nop 1
	v_permlane16_swap_b32_e32 v228, v230
	v_permlane16_swap_b32_e32 v229, v231
	v_lshl_add_u64 v[232:233], v[68:69], 0, v[234:235]
	global_store_dwordx4 v[232:233], v[228:231], off offset:256
	v_mov_b32_e32 v46, v241
	v_mad_i64_i32 v[48:49], s[0:1], v56, s52, v[146:147]
	v_lshl_add_u64 v[48:49], v[48:49], 0, s[26:27]
	v_lshl_add_u64 v[48:49], v[48:49], 0, v[134:135]
	s_nop 0
	v_pk_mul_f32 v[52:53], v[52:53], v[46:47] op_sel_hi:[1,0]
	v_pk_mul_f32 v[46:47], v[50:51], v[46:47] op_sel_hi:[1,0]
	s_nop 0
	v_cvt_pk_bf16_f32 v224, v46, v47
	v_cvt_pk_bf16_f32 v225, v52, v53
	s_nop 0
	v_mov_b32_e32 v46, v241
	s_nop 0
	v_pk_mul_f32 v[42:43], v[42:43], v[46:47] op_sel_hi:[1,0]
	v_pk_mul_f32 v[44:45], v[44:45], v[46:47] op_sel_hi:[1,0]
	v_cvt_pk_bf16_f32 v226, v42, v43
	s_nop 0
	v_cvt_pk_bf16_f32 v227, v44, v45
	s_nop 1
	v_permlane16_swap_b32_e32 v224, v226
	v_permlane16_swap_b32_e32 v225, v227
	v_lshl_add_u64 v[232:233], v[48:49], 0, v[234:235]
	global_store_dwordx4 v[232:233], v[224:227], off
	v_mov_b32_e32 v42, v241
	s_nop 0
	v_pk_mul_f32 v[38:39], v[38:39], v[42:43] op_sel_hi:[1,0]
	v_pk_mul_f32 v[40:41], v[40:41], v[42:43] op_sel_hi:[1,0]
	v_cvt_pk_bf16_f32 v228, v38, v39
	s_nop 0
	v_cvt_pk_bf16_f32 v229, v40, v41
	s_nop 0
	v_mov_b32_e32 v38, v241
	v_add_u32_e32 v40, 0xa0, v144
	v_ashrrev_i32_e32 v41, 31, v40
	v_lshl_add_u64 v[42:43], v[40:41], 2, s[12:13]
	s_nop 0
	v_pk_mul_f32 v[30:31], v[30:31], v[38:39] op_sel_hi:[1,0]
	v_pk_mul_f32 v[32:33], v[32:33], v[38:39] op_sel_hi:[1,0]
	v_cvt_pk_bf16_f32 v230, v30, v31
	s_nop 0
	v_cvt_pk_bf16_f32 v231, v32, v33
	s_nop 1
	v_permlane16_swap_b32_e32 v228, v230
	v_permlane16_swap_b32_e32 v229, v231
	v_lshl_add_u64 v[232:233], v[48:49], 0, v[234:235]
	global_store_dwordx4 v[232:233], v[228:231], off offset:256
	v_mov_b32_e32 v30, v242
	v_mad_i64_i32 v[32:33], s[0:1], v40, s52, v[146:147]
	v_lshl_add_u64 v[32:33], v[32:33], 0, s[26:27]
	v_lshl_add_u64 v[32:33], v[32:33], 0, v[134:135]
	s_nop 0
	v_pk_mul_f32 v[36:37], v[36:37], v[30:31] op_sel_hi:[1,0]
	v_pk_mul_f32 v[30:31], v[34:35], v[30:31] op_sel_hi:[1,0]
	s_nop 0
	v_cvt_pk_bf16_f32 v224, v30, v31
	v_cvt_pk_bf16_f32 v225, v36, v37
	s_nop 0
	v_mov_b32_e32 v30, v242
	s_nop 0
	v_pk_mul_f32 v[26:27], v[26:27], v[30:31] op_sel_hi:[1,0]
	v_pk_mul_f32 v[28:29], v[28:29], v[30:31] op_sel_hi:[1,0]
	v_cvt_pk_bf16_f32 v226, v26, v27
	s_nop 0
	v_cvt_pk_bf16_f32 v227, v28, v29
	s_nop 1
	v_permlane16_swap_b32_e32 v224, v226
	v_permlane16_swap_b32_e32 v225, v227
	v_lshl_add_u64 v[232:233], v[32:33], 0, v[234:235]
	global_store_dwordx4 v[232:233], v[224:227], off
	v_mov_b32_e32 v26, v242
	s_nop 0
	v_pk_mul_f32 v[22:23], v[22:23], v[26:27] op_sel_hi:[1,0]
	v_pk_mul_f32 v[24:25], v[24:25], v[26:27] op_sel_hi:[1,0]
	v_cvt_pk_bf16_f32 v228, v22, v23
	s_nop 0
	v_cvt_pk_bf16_f32 v229, v24, v25
	s_nop 0
	v_mov_b32_e32 v22, v242
	v_add_u32_e32 v24, 0xb0, v144
	v_ashrrev_i32_e32 v25, 31, v24
	v_lshl_add_u64 v[26:27], v[24:25], 2, s[12:13]
	s_nop 0
	v_pk_mul_f32 v[14:15], v[14:15], v[22:23] op_sel_hi:[1,0]
	v_pk_mul_f32 v[16:17], v[16:17], v[22:23] op_sel_hi:[1,0]
	v_cvt_pk_bf16_f32 v230, v14, v15
	s_nop 0
	v_cvt_pk_bf16_f32 v231, v16, v17
	s_nop 1
	v_permlane16_swap_b32_e32 v228, v230
	v_permlane16_swap_b32_e32 v229, v231
	v_lshl_add_u64 v[232:233], v[32:33], 0, v[234:235]
	global_store_dwordx4 v[232:233], v[228:231], off offset:256
	v_mov_b32_e32 v14, v243
	v_mad_i64_i32 v[16:17], s[0:1], v24, s52, v[146:147]
	v_lshl_add_u64 v[16:17], v[16:17], 0, s[26:27]
	v_lshl_add_u64 v[16:17], v[16:17], 0, v[134:135]
	s_nop 0
	v_pk_mul_f32 v[20:21], v[20:21], v[14:15] op_sel_hi:[1,0]
	v_pk_mul_f32 v[14:15], v[18:19], v[14:15] op_sel_hi:[1,0]
	s_nop 0
	v_cvt_pk_bf16_f32 v224, v14, v15
	v_cvt_pk_bf16_f32 v225, v20, v21
	s_nop 0
	v_mov_b32_e32 v14, v243
	s_nop 0
	v_pk_mul_f32 v[10:11], v[10:11], v[14:15] op_sel_hi:[1,0]
	v_pk_mul_f32 v[12:13], v[12:13], v[14:15] op_sel_hi:[1,0]
	v_cvt_pk_bf16_f32 v226, v10, v11
	s_nop 0
	v_cvt_pk_bf16_f32 v227, v12, v13
	s_nop 1
	v_permlane16_swap_b32_e32 v224, v226
	v_permlane16_swap_b32_e32 v225, v227
	v_lshl_add_u64 v[232:233], v[16:17], 0, v[234:235]
	global_store_dwordx4 v[232:233], v[224:227], off
	v_mov_b32_e32 v10, v243
	s_nop 0
	v_pk_mul_f32 v[6:7], v[6:7], v[10:11] op_sel_hi:[1,0]
	v_pk_mul_f32 v[8:9], v[8:9], v[10:11] op_sel_hi:[1,0]
	v_cvt_pk_bf16_f32 v228, v6, v7
	s_nop 0
	v_cvt_pk_bf16_f32 v229, v8, v9
	s_nop 0
	v_mov_b32_e32 v6, v243
	s_nop 0
	v_pk_mul_f32 v[2:3], v[2:3], v[6:7] op_sel_hi:[1,0]
	v_pk_mul_f32 v[4:5], v[4:5], v[6:7] op_sel_hi:[1,0]
	v_cvt_pk_bf16_f32 v230, v2, v3
	s_nop 0
	v_cvt_pk_bf16_f32 v231, v4, v5
	s_nop 1
	v_permlane16_swap_b32_e32 v228, v230
	v_permlane16_swap_b32_e32 v229, v231
	v_lshl_add_u64 v[232:233], v[16:17], 0, v[234:235]
	global_store_dwordx4 v[232:233], v[228:231], off offset:256
	s_cbranch_vccnz .LBB0_2694
	s_andn2_b64 vcc, exec, s[8:9]
	s_cbranch_vccnz .LBB0_2693
	s_barrier
	s_branch .LBB0_2693
